# barrier: release XGEN before leader acquire; rs-table loads batched; G1 preheader vmcnt0 removed
# baseline (speedup 1.0000x reference)
; DI unsigned xb_ld(unsigned* p)              { return __hip_atomic_load(p, __ATOMIC_RELAXED, __HIP_MEMORY_SCOPE_AGENT); }
; DI unsigned xb_add(unsigned* p, unsigned v) { return __hip_atomic_fetch_add(p, v, __ATOMIC_RELAXED, __HIP_MEMORY_SCOPE_AGENT); }
; #define XB_SPIN(cond, bar) do { unsigned _sp = 0; while (cond) { __builtin_amdgcn_s_sleep(1); \
;     if ((++_sp & 255u) == 0u) { if (xb_ld(&(bar)[XB_TMO])) break; if (_sp > XB_SPIN_CAP) { atomicAdd(&(bar)[XB_TMO], 1u); break; } } } } while (0)
; DI void xcd_barrier(const XcdBarrier& b) {
;     ...
;             __builtin_amdgcn_fence(__ATOMIC_ACQUIRE, "agent");
;             xb_add(&bar[XB_XGEN(b.x)], 1u);
;             asm volatile("s_waitcnt vmcnt(0)" ::: "memory");
;         } else {
;             XB_SPIN(xb_ld(&bar[XB_XGEN(b.x)]) == gen, bar);
;             __builtin_amdgcn_fence(__ATOMIC_ACQUIRE, "agent");
;             asm volatile("s_waitcnt vmcnt(0)" ::: "memory");
;         }
;     }
;     __syncthreads();
.LBB0_202:
	s_or_b64 exec, exec, s[4:5]
	s_mov_b64 s[4:5], exec
	v_mbcnt_lo_u32_b32 v1, s4, 0
	v_mbcnt_hi_u32_b32 v1, s5, v1
	v_cmp_eq_u32_e32 vcc, 0, v1
	s_and_saveexec_b64 s[6:7], vcc
	s_cbranch_execz .LBB0_204
	s_bcnt1_i32_b64 s4, s[4:5]
	v_mov_b32_e32 v1, 0x2000
	v_mov_b32_e32 v2, s4
	global_atomic_add v1, v2, s[2:3] offset:1024
.LBB0_204:
	s_or_b64 exec, exec, s[6:7]
	s_waitcnt vmcnt(0)
	buffer_inv sc1
	s_waitcnt vmcnt(0)
.LBB0_205:
	s_or_b64 exec, exec, s[0:1]
	s_waitcnt lgkmcnt(0)
	s_barrier

; #define LAS __attribute__((address_space(3)))
; DI unsigned xb_ld(unsigned* p)              { return __hip_atomic_load(p, __ATOMIC_RELAXED, __HIP_MEMORY_SCOPE_AGENT); }
; DI unsigned xb_add(unsigned* p, unsigned v) { return __hip_atomic_fetch_add(p, v, __ATOMIC_RELAXED, __HIP_MEMORY_SCOPE_AGENT); }
; #define XB_SPIN(cond, bar) do { unsigned _sp = 0; while (cond) { __builtin_amdgcn_s_sleep(1); \
;     if ((++_sp & 255u) == 0u) { if (xb_ld(&(bar)[XB_TMO])) break; if (_sp > XB_SPIN_CAP) { atomicAdd(&(bar)[XB_TMO], 1u); break; } } } } while (0)
; DI void xcd_barrier(const XcdBarrier& b) {
;     ...
;             __builtin_amdgcn_fence(__ATOMIC_ACQUIRE, "agent");
;             xb_add(&bar[XB_XGEN(b.x)], 1u);
;             asm volatile("s_waitcnt vmcnt(0)" ::: "memory");
;         } else {
;             XB_SPIN(xb_ld(&bar[XB_XGEN(b.x)]) == gen, bar);
;             __builtin_amdgcn_fence(__ATOMIC_ACQUIRE, "agent");
;             asm volatile("s_waitcnt vmcnt(0)" ::: "memory");
;         }
;     }
;     __syncthreads();
; DI void fill_rs_table(const Frame& F, const pg8::Sched& S, const float* RSTD) {
;     LAS float* rs = (LAS float*)(F.lds + LDS_RS);
;     for (int i = 0; i < 9; ++i) { pg8::Unit u; if (!S.next(i, u)) break;
;         if (u.kind == 0 && F.tid < 256) rs[i * 256 + F.tid] = RSTD[u.pm * 256 + F.tid]; }
.LBB0_284:
	s_or_b64 exec, exec, s[4:5]
	s_mov_b64 s[4:5], exec
	v_mbcnt_lo_u32_b32 v3, s4, 0
	v_mbcnt_hi_u32_b32 v3, s5, v3
	v_cmp_eq_u32_e32 vcc, 0, v3
	s_and_saveexec_b64 s[6:7], vcc
	s_cbranch_execz .LBB0_286
	s_bcnt1_i32_b64 s4, s[4:5]
	v_mov_b32_e32 v3, s4
	v_readlane_b32 s4, v253, 48
	v_readlane_b32 s5, v253, 49
	s_nop 4
	global_atomic_add v2, v3, s[4:5]
.LBB0_286:
	s_or_b64 exec, exec, s[6:7]
	s_waitcnt vmcnt(0)
	buffer_inv sc1
	s_waitcnt vmcnt(0)
.LBB0_287:
	s_or_b64 exec, exec, s[2:3]
	s_waitcnt lgkmcnt(0)
	s_barrier
.LBB0_288:
	s_cmp_le_i32 s70, s18
	s_cselect_b64 s[2:3], -1, 0
	s_and_b64 s[0:1], s[2:3], s[0:1]
	s_andn2_b64 vcc, exec, s[0:1]
	s_mul_i32 s2, s90, 0x3b00000
	v_writelane_b32 v249, s2, 25
	s_cbranch_vccnz .LBB0_332
	s_cmpk_lt_i32 s69, 0x900
	s_cselect_b64 s[4:5], -1, 0
	s_cmpk_gt_i32 s69, 0x8ff
	s_cbranch_scc1 .LBB0_316
	s_mul_i32 s62, s90, 0x12000
	s_lshl_b64 s[2:3], s[62:63], 2
	s_add_u32 s2, s96, s2
	s_addc_u32 s3, s97, s3
	s_add_u32 s6, s2, 0x25600000
	v_readlane_b32 s2, v252, 56
	s_addc_u32 s7, s3, 0
	s_nop 0
	v_lshl_add_u32 v3, v0, 2, s2
	s_movk_i32 s2, 0xff
	v_cmp_lt_i32_e32 vcc, s2, v0
	s_movk_i32 s2, 0x100
	v_cmp_gt_i32_e64 s[2:3], s2, v0
	s_and_saveexec_b64 s[8:9], s[2:3]
	s_cbranch_execz .LBB0_292
	s_ashr_i32 s10, s69, 31
	s_lshr_b32 s10, s10, 29
	s_add_i32 s10, s69, s10
	s_and_b32 s11, s10, -8
	s_sub_i32 s11, s69, s11
	s_cmp_lt_i32 s11, 0
	s_movk_i32 s12, 0x121
	s_cselect_b32 s12, s12, 0x120
	s_mul_i32 s11, s11, s12
	s_ashr_i32 s10, s10, 3
	s_add_i32 s10, s11, s10
	s_ashr_i32 s11, s10, 31
	s_lshr_b32 s11, s11, 24
	s_add_i32 s11, s10, s11
	s_and_b32 s12, s11, 0xff00
	s_sub_i32 s10, s10, s12
	s_sext_i32_i16 s12, s10
	s_bfe_u32 s12, s12, 0x3001c
	s_add_i32 s12, s10, s12
	s_and_b32 s12, s12, 0xfff8
	s_sub_i32 s10, s10, s12
	s_sext_i32_i16 s10, s10
	s_lshl_b32 s11, s11, 3
	s_and_b32 s11, s11, 0xfffff800
	s_lshl_b32 s10, s10, 8
	s_add_i32 s10, s10, s11
	v_add_u32_e32 v4, s10, v0
	s_waitcnt lgkmcnt(0)
	v_ashrrev_i32_e32 v5, 31, v4
	v_lshl_add_u64 v[4:5], v[4:5], 2, s[6:7]
	global_load_dword v230, v[4:5], off
.LBB0_292:
	s_or_b64 exec, exec, s[8:9]
	s_add_i32 s10, s69, s76
	s_cmpk_gt_i32 s10, 0x8ff
	s_cbranch_scc1 .Lrs_flush_0
	s_and_saveexec_b64 s[8:9], s[2:3]
	s_cbranch_execz .LBB0_295
	s_ashr_i32 s11, s10, 31
	s_lshr_b32 s11, s11, 29
	s_add_i32 s11, s10, s11
	s_ashr_i32 s12, s11, 3
	s_and_b32 s11, s11, -8
	s_sub_i32 s11, s10, s11
	s_cmp_lt_i32 s11, 0
	s_movk_i32 s13, 0x121
	s_cselect_b32 s13, s13, 0x120
	s_mul_i32 s11, s11, s13
	s_add_i32 s11, s11, s12
	s_ashr_i32 s12, s11, 31
	s_lshr_b32 s12, s12, 24
	s_add_i32 s12, s11, s12
	s_and_b32 s13, s12, 0xff00
	s_sub_i32 s11, s11, s13
	s_sext_i32_i16 s13, s11
	s_bfe_u32 s13, s13, 0x3001c
	s_add_i32 s13, s11, s13
	s_and_b32 s13, s13, 0xfff8
	s_sub_i32 s11, s11, s13
	s_sext_i32_i16 s11, s11
	s_lshl_b32 s12, s12, 3
	s_and_b32 s12, s12, 0xfffff800
	s_lshl_b32 s11, s11, 8
	s_add_i32 s11, s11, s12
	v_add_u32_e32 v4, s11, v0
	s_waitcnt lgkmcnt(0)
	v_ashrrev_i32_e32 v5, 31, v4
	v_lshl_add_u64 v[4:5], v[4:5], 2, s[6:7]
	global_load_dword v231, v[4:5], off
.LBB0_295:
	s_or_b64 exec, exec, s[8:9]
	s_add_i32 s10, s10, s76
	s_cmpk_gt_i32 s10, 0x8ff
	s_cbranch_scc1 .Lrs_flush_0
	s_and_saveexec_b64 s[8:9], s[2:3]
	s_cbranch_execz .LBB0_298
	s_ashr_i32 s11, s10, 31
	s_lshr_b32 s11, s11, 29
	s_add_i32 s11, s10, s11
	s_ashr_i32 s12, s11, 3
	s_and_b32 s11, s11, -8
	s_sub_i32 s11, s10, s11
	s_cmp_lt_i32 s11, 0
	s_movk_i32 s13, 0x121
	s_cselect_b32 s13, s13, 0x120
	s_mul_i32 s11, s11, s13
	s_add_i32 s11, s11, s12
	s_ashr_i32 s12, s11, 31
	s_lshr_b32 s12, s12, 24
	s_add_i32 s12, s11, s12
	s_and_b32 s13, s12, 0xff00
	s_sub_i32 s11, s11, s13
	s_sext_i32_i16 s13, s11
	s_bfe_u32 s13, s13, 0x3001c
	s_add_i32 s13, s11, s13
	s_and_b32 s13, s13, 0xfff8
	s_sub_i32 s11, s11, s13
	s_sext_i32_i16 s11, s11
	s_lshl_b32 s12, s12, 3
	s_and_b32 s12, s12, 0xfffff800
	s_lshl_b32 s11, s11, 8
	s_add_i32 s11, s11, s12
	v_add_u32_e32 v4, s11, v0
	s_waitcnt lgkmcnt(0)
	v_ashrrev_i32_e32 v5, 31, v4
	v_lshl_add_u64 v[4:5], v[4:5], 2, s[6:7]
	global_load_dword v232, v[4:5], off
.LBB0_298:
	s_or_b64 exec, exec, s[8:9]
	s_add_i32 s10, s10, s76
	s_cmpk_gt_i32 s10, 0x8ff
	s_cbranch_scc1 .Lrs_flush_0
	s_and_saveexec_b64 s[8:9], s[2:3]
	s_cbranch_execz .LBB0_301
	s_ashr_i32 s11, s10, 31
	s_lshr_b32 s11, s11, 29
	s_add_i32 s11, s10, s11
	s_ashr_i32 s12, s11, 3
	s_and_b32 s11, s11, -8
	s_sub_i32 s11, s10, s11
	s_cmp_lt_i32 s11, 0
	s_movk_i32 s13, 0x121
	s_cselect_b32 s13, s13, 0x120
	s_mul_i32 s11, s11, s13
	s_add_i32 s11, s11, s12
	s_ashr_i32 s12, s11, 31
	s_lshr_b32 s12, s12, 24
	s_add_i32 s12, s11, s12
	s_and_b32 s13, s12, 0xff00
	s_sub_i32 s11, s11, s13
	s_sext_i32_i16 s13, s11
	s_bfe_u32 s13, s13, 0x3001c
	s_add_i32 s13, s11, s13
	s_and_b32 s13, s13, 0xfff8
	s_sub_i32 s11, s11, s13
	s_sext_i32_i16 s11, s11
	s_lshl_b32 s12, s12, 3
	s_and_b32 s12, s12, 0xfffff800
	s_lshl_b32 s11, s11, 8
	s_add_i32 s11, s11, s12
	v_add_u32_e32 v4, s11, v0
	s_waitcnt lgkmcnt(0)
	v_ashrrev_i32_e32 v5, 31, v4
	v_lshl_add_u64 v[4:5], v[4:5], 2, s[6:7]
	global_load_dword v233, v[4:5], off
; #define LAS __attribute__((address_space(3)))
; DI void fill_rs_table(const Frame& F, const pg8::Sched& S, const float* RSTD) {
;     LAS float* rs = (LAS float*)(F.lds + LDS_RS);
;     for (int i = 0; i < 9; ++i) { pg8::Unit u; if (!S.next(i, u)) break;
;         if (u.kind == 0 && F.tid < 256) rs[i * 256 + F.tid] = RSTD[u.pm * 256 + F.tid]; }
.LBB0_301:
	s_or_b64 exec, exec, s[8:9]
	s_add_i32 s10, s10, s76
	s_cmpk_gt_i32 s10, 0x8ff
	s_cbranch_scc1 .Lrs_flush_0
	s_and_saveexec_b64 s[8:9], s[2:3]
	s_cbranch_execz .LBB0_304
	s_ashr_i32 s11, s10, 31
	s_lshr_b32 s11, s11, 29
	s_add_i32 s11, s10, s11
	s_ashr_i32 s12, s11, 3
	s_and_b32 s11, s11, -8
	s_sub_i32 s11, s10, s11
	s_cmp_lt_i32 s11, 0
	s_movk_i32 s13, 0x121
	s_cselect_b32 s13, s13, 0x120
	s_mul_i32 s11, s11, s13
	s_add_i32 s11, s11, s12
	s_ashr_i32 s12, s11, 31
	s_lshr_b32 s12, s12, 24
	s_add_i32 s12, s11, s12
	s_and_b32 s13, s12, 0xff00
	s_sub_i32 s11, s11, s13
	s_sext_i32_i16 s13, s11
	s_bfe_u32 s13, s13, 0x3001c
	s_add_i32 s13, s11, s13
	s_and_b32 s13, s13, 0xfff8
	s_sub_i32 s11, s11, s13
	s_sext_i32_i16 s11, s11
	s_lshl_b32 s12, s12, 3
	s_and_b32 s12, s12, 0xfffff800
	s_lshl_b32 s11, s11, 8
	s_add_i32 s11, s11, s12
	v_add_u32_e32 v4, s11, v0
	s_waitcnt lgkmcnt(0)
	v_ashrrev_i32_e32 v5, 31, v4
	v_lshl_add_u64 v[4:5], v[4:5], 2, s[6:7]
	global_load_dword v234, v[4:5], off
.LBB0_304:
	s_or_b64 exec, exec, s[8:9]
	s_add_i32 s10, s10, s76
	s_cmpk_gt_i32 s10, 0x8ff
	s_cbranch_scc1 .Lrs_flush_0
	s_and_saveexec_b64 s[8:9], s[2:3]
	s_cbranch_execz .LBB0_307
	s_ashr_i32 s11, s10, 31
	s_lshr_b32 s11, s11, 29
	s_add_i32 s11, s10, s11
	s_ashr_i32 s12, s11, 3
	s_and_b32 s11, s11, -8
	s_sub_i32 s11, s10, s11
	s_cmp_lt_i32 s11, 0
	s_movk_i32 s13, 0x121
	s_cselect_b32 s13, s13, 0x120
	s_mul_i32 s11, s11, s13
	s_add_i32 s11, s11, s12
	s_ashr_i32 s12, s11, 31
	s_lshr_b32 s12, s12, 24
	s_add_i32 s12, s11, s12
	s_and_b32 s13, s12, 0xff00
	s_sub_i32 s11, s11, s13
	s_sext_i32_i16 s13, s11
	s_bfe_u32 s13, s13, 0x3001c
	s_add_i32 s13, s11, s13
	s_and_b32 s13, s13, 0xfff8
	s_sub_i32 s11, s11, s13
	s_sext_i32_i16 s11, s11
	s_lshl_b32 s12, s12, 3
	s_and_b32 s12, s12, 0xfffff800
	s_lshl_b32 s11, s11, 8
	s_add_i32 s11, s11, s12
	v_add_u32_e32 v4, s11, v0
	s_waitcnt lgkmcnt(0)
	v_ashrrev_i32_e32 v5, 31, v4
	v_lshl_add_u64 v[4:5], v[4:5], 2, s[6:7]
	global_load_dword v235, v[4:5], off
.LBB0_307:
	s_or_b64 exec, exec, s[8:9]
	s_add_i32 s10, s10, s76
	s_cmpk_gt_i32 s10, 0x8ff
	s_cbranch_scc1 .Lrs_flush_0
	s_and_saveexec_b64 s[8:9], s[2:3]
	s_cbranch_execz .LBB0_310
	s_ashr_i32 s11, s10, 31
	s_lshr_b32 s11, s11, 29
	s_add_i32 s11, s10, s11
	s_ashr_i32 s12, s11, 3
	s_and_b32 s11, s11, -8
	s_sub_i32 s11, s10, s11
	s_cmp_lt_i32 s11, 0
	s_movk_i32 s13, 0x121
	s_cselect_b32 s13, s13, 0x120
	s_mul_i32 s11, s11, s13
	s_add_i32 s11, s11, s12
	s_ashr_i32 s12, s11, 31
	s_lshr_b32 s12, s12, 24
	s_add_i32 s12, s11, s12
	s_and_b32 s13, s12, 0xff00
	s_sub_i32 s11, s11, s13
	s_sext_i32_i16 s13, s11
	s_bfe_u32 s13, s13, 0x3001c
	s_add_i32 s13, s11, s13
	s_and_b32 s13, s13, 0xfff8
	s_sub_i32 s11, s11, s13
	s_sext_i32_i16 s11, s11
	s_lshl_b32 s12, s12, 3
	s_and_b32 s12, s12, 0xfffff800
	s_lshl_b32 s11, s11, 8
	s_add_i32 s11, s11, s12
	v_add_u32_e32 v4, s11, v0
	s_waitcnt lgkmcnt(0)
	v_ashrrev_i32_e32 v5, 31, v4
	v_lshl_add_u64 v[4:5], v[4:5], 2, s[6:7]
	global_load_dword v236, v[4:5], off
.LBB0_310:
	s_or_b64 exec, exec, s[8:9]
	s_add_i32 s10, s10, s76
	s_cmpk_gt_i32 s10, 0x8ff
	s_cbranch_scc1 .Lrs_flush_0
	s_and_saveexec_b64 s[8:9], s[2:3]
	s_cbranch_execz .LBB0_313
	s_ashr_i32 s2, s10, 31
	s_lshr_b32 s2, s2, 29
	s_add_i32 s2, s10, s2
	s_ashr_i32 s3, s2, 3
	s_and_b32 s2, s2, -8
	s_sub_i32 s2, s10, s2
	s_cmp_lt_i32 s2, 0
	s_movk_i32 s11, 0x121
	s_cselect_b32 s11, s11, 0x120
	s_mul_i32 s2, s2, s11
	s_add_i32 s2, s2, s3
	s_ashr_i32 s3, s2, 31
	s_lshr_b32 s3, s3, 24
	s_add_i32 s3, s2, s3
	s_and_b32 s11, s3, 0xff00
	s_sub_i32 s2, s2, s11
	s_sext_i32_i16 s11, s2
	s_bfe_u32 s11, s11, 0x3001c
	s_add_i32 s11, s2, s11
	s_and_b32 s11, s11, 0xfff8
	s_sub_i32 s2, s2, s11
	s_sext_i32_i16 s2, s2
	s_lshl_b32 s3, s3, 3
	s_and_b32 s3, s3, 0xfffff800
	s_lshl_b32 s2, s2, 8
	s_add_i32 s2, s2, s3
	v_add_u32_e32 v4, s2, v0
	s_waitcnt lgkmcnt(0)
	v_ashrrev_i32_e32 v5, 31, v4
	v_lshl_add_u64 v[4:5], v[4:5], 2, s[6:7]
	global_load_dword v237, v[4:5], off
.LBB0_313:
	s_or_b64 exec, exec, s[8:9]
	s_add_i32 s8, s10, s76
	s_cmpk_lt_i32 s8, 0x900
	s_cselect_b64 s[2:3], -1, 0
	s_xor_b64 s[10:11], vcc, -1
	s_and_b64 s[10:11], s[2:3], s[10:11]
	s_and_saveexec_b64 s[2:3], s[10:11]
	s_cbranch_execz .LBB0_315
	s_ashr_i32 s9, s8, 31
	s_lshr_b32 s9, s9, 29
	s_add_i32 s9, s8, s9
	s_ashr_i32 s10, s9, 3
	s_and_b32 s9, s9, -8
	s_sub_i32 s8, s8, s9
	s_cmp_lt_i32 s8, 0
	s_movk_i32 s9, 0x121
	s_cselect_b32 s9, s9, 0x120
	s_mul_i32 s8, s8, s9
	s_add_i32 s8, s8, s10
	s_ashr_i32 s9, s8, 31
	s_lshr_b32 s9, s9, 24
	s_add_i32 s9, s8, s9
	s_and_b32 s10, s9, 0xff00
	s_sub_i32 s8, s8, s10
	s_sext_i32_i16 s10, s8
	s_bfe_u32 s10, s10, 0x3001c
	s_add_i32 s10, s8, s10
	s_and_b32 s10, s10, 0xfff8
	s_sub_i32 s8, s8, s10
	s_sext_i32_i16 s8, s8
	s_lshl_b32 s9, s9, 3
	s_and_b32 s9, s9, 0xfffff800
	s_lshl_b32 s8, s8, 8
	s_add_i32 s8, s8, s9
	v_add_u32_e32 v4, s8, v0
	s_waitcnt lgkmcnt(0)
	v_ashrrev_i32_e32 v5, 31, v4
	v_lshl_add_u64 v[4:5], v[4:5], 2, s[6:7]
	global_load_dword v238, v[4:5], off

; DI void fill_rs_table(const Frame& F, const pg8::Sched& S, const float* RSTD) {
;     ...
;     for (int i = 0; i < 9; ++i) { pg8::Unit u; if (!S.next(i, u)) break;
;         if (u.kind == 0 && F.tid < 256) rs[i * 256 + F.tid] = RSTD[u.pm * 256 + F.tid]; }
;     __syncthreads();
.Lrs_flush_0:
	s_movk_i32 s100, 0x100
	v_cmp_gt_i32_e64 s[100:101], s100, v0
	s_waitcnt vmcnt(0)
	s_and_saveexec_b64 s[100:101], s[100:101]
	ds_write_b32 v3, v230
	ds_write_b32 v3, v231 offset:1024
	ds_write_b32 v3, v232 offset:2048
	ds_write_b32 v3, v233 offset:3072
	ds_write_b32 v3, v234 offset:4096
	ds_write_b32 v3, v235 offset:5120
	ds_write_b32 v3, v236 offset:6144
	ds_write_b32 v3, v237 offset:7168
	ds_write_b32 v3, v238 offset:8192
	s_or_b64 exec, exec, s[100:101]

; #define PG8_STAGE(bufoff, gbase, voff) do { _Pragma("unroll") for (int _i = 0; _i < 2; ++_i) \
;         __builtin_amdgcn_global_load_lds((const unsigned*)((const char*)(gbase) + (voff)[_i]), (LAS unsigned*)(lds + (bufoff) + ldsw + _i * 8192), 16, 0, 0); } while (0)
; #define PG8_WAIT_V(n) asm volatile("s_waitcnt vmcnt(" #n ")" ::: "memory")
; #define PG8_BAR __builtin_amdgcn_s_barrier()
; template <class Epi, bool ALIGN_EPI>
; DI void gemm_phase(LAS unsigned char* lds, const Sched& S, const Epi& E, int tid) {
;     const int wid = __builtin_amdgcn_readfirstlane(tid >> 6), lane = tid & 63, wr = wid >> 2, wc = wid & 3, fr = lane & 15, fq = lane >> 4;
;     const int lda = S.lda, ldb = S.ldb;
;     unsigned voffA[2], voffB[2];
; #pragma unroll
;     for (int i = 0; i < 2; ++i) { int R, C; stage_rc(tid * 16 + i * 8192, R, C); const int Rb = (R & ~31) + perm32(R & 31);
;         voffA[i] = (unsigned)(R * lda + C) * 2u; voffB[i] = (unsigned)(Rb * ldb + C) * 2u; }
;     const size_t kstep = (size_t)(BK * 2);
;     const size_t hstepA = (size_t)HALF * lda * 2, hstepB = (size_t)HALF * ldb * 2;
;     const unsigned ldsw = (unsigned)wid * 1024u;
;     const int aoff = lds_byte(wr * 64 + fr, fq * 8), boff = lds_byte(wc * 32 + fr, fq * 8);
;     ...
;     Unit cur, nxt; int ui = 0;
;     if (!S.next(0, cur)) return;
;     f32x4 acc[2][2][4][2];
; #pragma unroll
;     for (int a = 0; a < 2; ++a)
; #pragma unroll
;         for (int b = 0; b < 2; ++b)
; #pragma unroll
;             for (int m = 0; m < 4; ++m)
; #pragma unroll
;                 for (int n = 0; n < 2; ++n) acc[a][b][m][n] = (f32x4){0.f, 0.f, 0.f, 0.f};
;     bf16x8 At[4][2], B0[2][2], B1[2][2];
;     const char* cA = cur.a; const char* cB = cur.b;
;     PG8_STAGE(PG8_SB(0, 0), cB, voffB); PG8_STAGE(PG8_SB(0, 1), cB + hstepB, voffB); PG8_STAGE(PG8_SA(0, 0), cA, voffA); PG8_STAGE(PG8_SA(0, 1), cA + hstepA, voffA);
;     if (wr == 1) PG8_BAR;
;     PG8_WAIT_V(2); PG8_BAR;
;     PG8_STAGE(PG8_SB(1, 0), cB + kstep, voffB); PG8_STAGE(PG8_SA(1, 0), cA + kstep, voffA); PG8_STAGE(PG8_SB(1, 1), cB + hstepB + kstep, voffB);
;     PG8_WAIT_V(6); PG8_BAR;
.LBB0_319:
	s_add_u32 s4, s96, 0x16b00000
	s_addc_u32 s5, s97, 0
	s_lshl_b32 s9, s9, 5
	s_and_b32 s9, s9, 0x60
	s_add_i32 m0, s17, 0x18000
	v_lshl_add_u64 v[10:11], v[10:11], 0, s[84:85]
	s_lshl_b32 s12, s8, 13
	s_lshl_b32 s13, s9, 7
	s_waitcnt vmcnt(2)
	s_barrier
	global_load_lds_dwordx4 v[10:11], off
	v_lshl_add_u64 v[8:9], v[8:9], 0, s[84:85]
	s_add_i32 m0, s17, 0x1a000
	s_add_i32 s39, s17, 0x8000
	s_add_i32 s40, s17, 0xa000
	global_load_lds_dwordx4 v[8:9], off
	v_lshl_add_u64 v[4:5], v[4:5], 0, s[84:85]
	s_mov_b32 m0, s39
	s_add_u32 s10, s24, 0x40080
	global_load_lds_dwordx4 v[4:5], off
	v_lshl_add_u64 v[4:5], v[6:7], 0, s[84:85]
	s_mov_b32 m0, s40
	s_addc_u32 s11, s25, 0
	global_load_lds_dwordx4 v[4:5], off
	s_add_i32 m0, s17, 0x1c000
	v_lshl_add_u64 v[4:5], s[10:11], 0, v[136:137]
	global_load_lds_dwordx4 v[4:5], off
	v_lshl_add_u64 v[4:5], s[10:11], 0, v[132:133]
	s_add_i32 m0, s17, 0x1e000
	s_sext_i32_i16 s43, s6
	global_load_lds_dwordx4 v[4:5], off
	v_lshrrev_b32_e32 v5, 1, v0
	v_and_b32_e32 v5, 24, v5
	s_lshl_b32 s6, s8, 8
	v_and_b32_e32 v4, 15, v0
	v_lshlrev_b32_e32 v6, 1, v5
	s_add_i32 s6, s6, 0
	v_lshl_or_b32 v3, s8, 6, v4
	v_lshl_or_b32 v6, v4, 6, v6
	v_lshlrev_b32_e32 v4, 2, v4
	s_add_i32 s6, s6, 0x20000
	v_and_b32_e32 v7, 32, v4
	v_add_u32_e32 v145, s6, v4
	v_lshlrev_b32_e32 v4, 14, v16
	v_and_b32_e32 v4, 0xffff8000, v4
	v_or_b32_e32 v146, s9, v5
	v_lshl_add_u32 v4, v15, 11, v4
	v_and_b32_e32 v5, 1, v16
	v_lshl_or_b32 v4, v5, 6, v4
	v_lshl_add_u32 v140, v17, 1, v4
	v_lshlrev_b32_e32 v4, 14, v12
	v_and_b32_e32 v4, 0xffff8000, v4
	s_waitcnt vmcnt(6)
	v_lshl_add_u32 v4, v13, 11, v4
	v_and_b32_e32 v5, 1, v12
	v_bitop3_b32 v8, v6, s12, v7 bitop3:0xde
	s_cmpk_lt_u32 s7, 0x100
	v_lshl_or_b32 v4, v5, 6, v4
	v_bitop3_b32 v144, s13, v6, v7 bitop3:0xf6
	s_cselect_b64 s[6:7], -1, 0
	v_mov_b32_e32 v141, v2
	v_lshl_add_u32 v142, v14, 1, v4
	v_mov_b32_e32 v143, v2
	s_mov_b32 s44, 0
	v_add_u32_e32 v147, 0, v8
	s_mov_b32 s41, 0
	s_barrier
	s_branch .LBB0_322

; DI unsigned xb_ld(unsigned* p)              { return __hip_atomic_load(p, __ATOMIC_RELAXED, __HIP_MEMORY_SCOPE_AGENT); }
; DI unsigned xb_add(unsigned* p, unsigned v) { return __hip_atomic_fetch_add(p, v, __ATOMIC_RELAXED, __HIP_MEMORY_SCOPE_AGENT); }
; #define XB_SPIN(cond, bar) do { unsigned _sp = 0; while (cond) { __builtin_amdgcn_s_sleep(1); \
;     if ((++_sp & 255u) == 0u) { if (xb_ld(&(bar)[XB_TMO])) break; if (_sp > XB_SPIN_CAP) { atomicAdd(&(bar)[XB_TMO], 1u); break; } } } } while (0)
; DI void xcd_barrier(const XcdBarrier& b) {
;     ...
;             __builtin_amdgcn_fence(__ATOMIC_ACQUIRE, "agent");
;             xb_add(&bar[XB_XGEN(b.x)], 1u);
;             asm volatile("s_waitcnt vmcnt(0)" ::: "memory");
;         } else {
;             XB_SPIN(xb_ld(&bar[XB_XGEN(b.x)]) == gen, bar);
;             __builtin_amdgcn_fence(__ATOMIC_ACQUIRE, "agent");
;             asm volatile("s_waitcnt vmcnt(0)" ::: "memory");
;         }
;     }
;     __syncthreads();
.LBB0_384:
	s_or_b64 exec, exec, s[6:7]
	s_waitcnt vmcnt(0)
	buffer_inv sc1
	s_waitcnt vmcnt(0)
.LBB0_385:
	s_or_b64 exec, exec, s[0:1]
	s_waitcnt lgkmcnt(0)
	s_barrier

; DI unsigned xb_ld(unsigned* p)              { return __hip_atomic_load(p, __ATOMIC_RELAXED, __HIP_MEMORY_SCOPE_AGENT); }
; DI unsigned xb_add(unsigned* p, unsigned v) { return __hip_atomic_fetch_add(p, v, __ATOMIC_RELAXED, __HIP_MEMORY_SCOPE_AGENT); }
; #define XB_SPIN(cond, bar) do { unsigned _sp = 0; while (cond) { __builtin_amdgcn_s_sleep(1); \
;     if ((++_sp & 255u) == 0u) { if (xb_ld(&(bar)[XB_TMO])) break; if (_sp > XB_SPIN_CAP) { atomicAdd(&(bar)[XB_TMO], 1u); break; } } } } while (0)
; DI void xcd_barrier(const XcdBarrier& b) {
;     ...
;             __builtin_amdgcn_fence(__ATOMIC_ACQUIRE, "agent");
;             xb_add(&bar[XB_XGEN(b.x)], 1u);
;             asm volatile("s_waitcnt vmcnt(0)" ::: "memory");
;         } else {
;             XB_SPIN(xb_ld(&bar[XB_XGEN(b.x)]) == gen, bar);
;             __builtin_amdgcn_fence(__ATOMIC_ACQUIRE, "agent");
;             asm volatile("s_waitcnt vmcnt(0)" ::: "memory");
;         }
;     }
;     __syncthreads();
.LBB0_492:
	s_or_b64 exec, exec, s[6:7]
	s_waitcnt vmcnt(0)
	buffer_inv sc1
	s_waitcnt vmcnt(0)
.LBB0_493:
	s_or_b64 exec, exec, s[0:1]
	s_waitcnt lgkmcnt(0)
	s_barrier

; DI unsigned xb_ld(unsigned* p)              { return __hip_atomic_load(p, __ATOMIC_RELAXED, __HIP_MEMORY_SCOPE_AGENT); }
; DI unsigned xb_add(unsigned* p, unsigned v) { return __hip_atomic_fetch_add(p, v, __ATOMIC_RELAXED, __HIP_MEMORY_SCOPE_AGENT); }
; #define XB_SPIN(cond, bar) do { unsigned _sp = 0; while (cond) { __builtin_amdgcn_s_sleep(1); \
;     if ((++_sp & 255u) == 0u) { if (xb_ld(&(bar)[XB_TMO])) break; if (_sp > XB_SPIN_CAP) { atomicAdd(&(bar)[XB_TMO], 1u); break; } } } } while (0)
; DI void xcd_barrier(const XcdBarrier& b) {
;     ...
;             __builtin_amdgcn_fence(__ATOMIC_ACQUIRE, "agent");
;             xb_add(&bar[XB_XGEN(b.x)], 1u);
;             asm volatile("s_waitcnt vmcnt(0)" ::: "memory");
;         } else {
;             XB_SPIN(xb_ld(&bar[XB_XGEN(b.x)]) == gen, bar);
;             __builtin_amdgcn_fence(__ATOMIC_ACQUIRE, "agent");
;             asm volatile("s_waitcnt vmcnt(0)" ::: "memory");
;         }
;     }
;     __syncthreads();
.LBB0_569:
	s_or_b64 exec, exec, s[6:7]
	s_waitcnt vmcnt(0)
	buffer_inv sc1
	s_waitcnt vmcnt(0)
.LBB0_570:
	s_or_b64 exec, exec, s[0:1]
	s_waitcnt lgkmcnt(0)
	s_barrier

; #define LAS __attribute__((address_space(3)))
; DI void fill_rs_table(const Frame& F, const pg8::Sched& S, const float* RSTD) {
;     LAS float* rs = (LAS float*)(F.lds + LDS_RS);
;     for (int i = 0; i < 9; ++i) { pg8::Unit u; if (!S.next(i, u)) break;
;         if (u.kind == 0 && F.tid < 256) rs[i * 256 + F.tid] = RSTD[u.pm * 256 + F.tid]; }
.LBB0_577:
	s_mul_i32 s62, s90, 0x12000
	s_lshl_b64 s[2:3], s[62:63], 2
	s_add_u32 s2, s96, s2
	s_addc_u32 s3, s97, s3
	s_add_u32 s6, s2, 0x25612000
	v_readlane_b32 s2, v252, 56
	s_addc_u32 s7, s3, 0
	s_nop 0
	v_lshl_add_u32 v3, v0, 2, s2
	s_movk_i32 s2, 0x100
	v_cmp_gt_i32_e64 s[2:3], s2, v0
	s_and_saveexec_b64 s[8:9], s[2:3]
	s_cbranch_execz .LBB0_579
	s_ashr_i32 s10, s10, 3
	s_add_i32 s10, s11, s10
	s_mul_hi_i32 s11, s10, 0x92492493
	s_add_i32 s11, s11, s10
	s_lshr_b32 s12, s11, 31
	s_ashr_i32 s11, s11, 5
	s_add_i32 s11, s11, s12
	s_mul_i32 s12, s11, 56
	s_sub_i32 s10, s10, s12
	s_bfe_i32 s12, s10, 0x80000
	s_bfe_u32 s12, s12, 0x3000c
	s_add_i32 s12, s10, s12
	s_and_b32 s12, s12, 0xf8
	s_sub_i32 s10, s10, s12
	s_sext_i32_i8 s10, s10
	s_lshl_b32 s11, s11, 11
	s_lshl_b32 s10, s10, 8
	s_add_i32 s10, s10, s11
	v_add_u32_e32 v4, s10, v0
	s_waitcnt lgkmcnt(0)
	v_ashrrev_i32_e32 v5, 31, v4
	v_lshl_add_u64 v[4:5], v[4:5], 2, s[6:7]
	global_load_dword v230, v[4:5], off

; #define LAS __attribute__((address_space(3)))
; DI void fill_rs_table(const Frame& F, const pg8::Sched& S, const float* RSTD) {
;     LAS float* rs = (LAS float*)(F.lds + LDS_RS);
;     for (int i = 0; i < 9; ++i) { pg8::Unit u; if (!S.next(i, u)) break;
;         if (u.kind == 0 && F.tid < 256) rs[i * 256 + F.tid] = RSTD[u.pm * 256 + F.tid]; }
.LBB0_583:
	s_ashr_i32 s11, s11, 3
	s_add_i32 s11, s12, s11
	s_mul_hi_i32 s12, s11, 0x92492493
	s_add_i32 s12, s12, s11
	s_lshr_b32 s13, s12, 31
	s_ashr_i32 s12, s12, 5
	s_add_i32 s12, s12, s13
	s_mul_i32 s13, s12, 56
	s_sub_i32 s11, s11, s13
	s_bfe_i32 s13, s11, 0x80000
	s_bfe_u32 s13, s13, 0x3000c
	s_add_i32 s13, s11, s13
	s_and_b32 s13, s13, 0xf8
	s_sub_i32 s11, s11, s13
	s_sext_i32_i8 s11, s11
	s_lshl_b32 s12, s12, 11
	s_lshl_b32 s11, s11, 8
	s_add_i32 s11, s11, s12
	v_add_u32_e32 v4, s11, v0
	s_waitcnt lgkmcnt(0)
	v_ashrrev_i32_e32 v5, 31, v4
	v_lshl_add_u64 v[4:5], v[4:5], 2, s[6:7]
	global_load_dword v231, v[4:5], off
	s_or_b64 exec, exec, s[8:9]
	s_add_i32 s10, s10, s76
	s_cmpk_gt_i32 s10, 0x1f7
	s_cbranch_scc1 .Lrs_flush_1
	s_branch .LBB0_587

; #define LAS __attribute__((address_space(3)))
; DI void fill_rs_table(const Frame& F, const pg8::Sched& S, const float* RSTD) {
;     LAS float* rs = (LAS float*)(F.lds + LDS_RS);
;     for (int i = 0; i < 9; ++i) { pg8::Unit u; if (!S.next(i, u)) break;
;         if (u.kind == 0 && F.tid < 256) rs[i * 256 + F.tid] = RSTD[u.pm * 256 + F.tid]; }
.LBB0_590:
	s_ashr_i32 s11, s11, 3
	s_add_i32 s11, s12, s11
	s_mul_hi_i32 s12, s11, 0x92492493
	s_add_i32 s12, s12, s11
	s_lshr_b32 s13, s12, 31
	s_ashr_i32 s12, s12, 5
	s_add_i32 s12, s12, s13
	s_mul_i32 s13, s12, 56
	s_sub_i32 s11, s11, s13
	s_bfe_i32 s13, s11, 0x80000
	s_bfe_u32 s13, s13, 0x3000c
	s_add_i32 s13, s11, s13
	s_and_b32 s13, s13, 0xf8
	s_sub_i32 s11, s11, s13
	s_sext_i32_i8 s11, s11
	s_lshl_b32 s12, s12, 11
	s_lshl_b32 s11, s11, 8
	s_add_i32 s11, s11, s12
	v_add_u32_e32 v4, s11, v0
	s_waitcnt lgkmcnt(0)
	v_ashrrev_i32_e32 v5, 31, v4
	v_lshl_add_u64 v[4:5], v[4:5], 2, s[6:7]
	global_load_dword v232, v[4:5], off
	s_or_b64 exec, exec, s[8:9]
	s_add_i32 s10, s10, s76
	s_cmpk_gt_i32 s10, 0x1f7
	s_cbranch_scc1 .Lrs_flush_1
	s_branch .LBB0_594

; #define LAS __attribute__((address_space(3)))
; DI void fill_rs_table(const Frame& F, const pg8::Sched& S, const float* RSTD) {
;     LAS float* rs = (LAS float*)(F.lds + LDS_RS);
;     for (int i = 0; i < 9; ++i) { pg8::Unit u; if (!S.next(i, u)) break;
;         if (u.kind == 0 && F.tid < 256) rs[i * 256 + F.tid] = RSTD[u.pm * 256 + F.tid]; }
.LBB0_597:
	s_ashr_i32 s11, s11, 3
	s_add_i32 s11, s12, s11
	s_mul_hi_i32 s12, s11, 0x92492493
	s_add_i32 s12, s12, s11
	s_lshr_b32 s13, s12, 31
	s_ashr_i32 s12, s12, 5
	s_add_i32 s12, s12, s13
	s_mul_i32 s13, s12, 56
	s_sub_i32 s11, s11, s13
	s_bfe_i32 s13, s11, 0x80000
	s_bfe_u32 s13, s13, 0x3000c
	s_add_i32 s13, s11, s13
	s_and_b32 s13, s13, 0xf8
	s_sub_i32 s11, s11, s13
	s_sext_i32_i8 s11, s11
	s_lshl_b32 s12, s12, 11
	s_lshl_b32 s11, s11, 8
	s_add_i32 s11, s11, s12
	v_add_u32_e32 v4, s11, v0
	s_waitcnt lgkmcnt(0)
	v_ashrrev_i32_e32 v5, 31, v4
	v_lshl_add_u64 v[4:5], v[4:5], 2, s[6:7]
	global_load_dword v233, v[4:5], off
	s_or_b64 exec, exec, s[8:9]
	s_add_i32 s10, s10, s76
	s_cmpk_gt_i32 s10, 0x1f7
	s_cbranch_scc1 .Lrs_flush_1
	s_branch .LBB0_601

; #define LAS __attribute__((address_space(3)))
; DI void fill_rs_table(const Frame& F, const pg8::Sched& S, const float* RSTD) {
;     LAS float* rs = (LAS float*)(F.lds + LDS_RS);
;     for (int i = 0; i < 9; ++i) { pg8::Unit u; if (!S.next(i, u)) break;
;         if (u.kind == 0 && F.tid < 256) rs[i * 256 + F.tid] = RSTD[u.pm * 256 + F.tid]; }
.LBB0_604:
	s_ashr_i32 s11, s11, 3
	s_add_i32 s11, s12, s11
	s_mul_hi_i32 s12, s11, 0x92492493
	s_add_i32 s12, s12, s11
	s_lshr_b32 s13, s12, 31
	s_ashr_i32 s12, s12, 5
	s_add_i32 s12, s12, s13
	s_mul_i32 s13, s12, 56
	s_sub_i32 s11, s11, s13
	s_bfe_i32 s13, s11, 0x80000
	s_bfe_u32 s13, s13, 0x3000c
	s_add_i32 s13, s11, s13
	s_and_b32 s13, s13, 0xf8
	s_sub_i32 s11, s11, s13
	s_sext_i32_i8 s11, s11
	s_lshl_b32 s12, s12, 11
	s_lshl_b32 s11, s11, 8
	s_add_i32 s11, s11, s12
	v_add_u32_e32 v4, s11, v0
	s_waitcnt lgkmcnt(0)
	v_ashrrev_i32_e32 v5, 31, v4
	v_lshl_add_u64 v[4:5], v[4:5], 2, s[6:7]
	global_load_dword v234, v[4:5], off
	s_or_b64 exec, exec, s[8:9]
	s_add_i32 s10, s10, s76
	s_cmpk_gt_i32 s10, 0x1f7
	s_cbranch_scc1 .Lrs_flush_1
	s_branch .LBB0_608

; #define LAS __attribute__((address_space(3)))
; DI void fill_rs_table(const Frame& F, const pg8::Sched& S, const float* RSTD) {
;     LAS float* rs = (LAS float*)(F.lds + LDS_RS);
;     for (int i = 0; i < 9; ++i) { pg8::Unit u; if (!S.next(i, u)) break;
;         if (u.kind == 0 && F.tid < 256) rs[i * 256 + F.tid] = RSTD[u.pm * 256 + F.tid]; }
.LBB0_611:
	s_ashr_i32 s11, s11, 3
	s_add_i32 s11, s12, s11
	s_mul_hi_i32 s12, s11, 0x92492493
	s_add_i32 s12, s12, s11
	s_lshr_b32 s13, s12, 31
	s_ashr_i32 s12, s12, 5
	s_add_i32 s12, s12, s13
	s_mul_i32 s13, s12, 56
	s_sub_i32 s11, s11, s13
	s_bfe_i32 s13, s11, 0x80000
	s_bfe_u32 s13, s13, 0x3000c
	s_add_i32 s13, s11, s13
	s_and_b32 s13, s13, 0xf8
	s_sub_i32 s11, s11, s13
	s_sext_i32_i8 s11, s11
	s_lshl_b32 s12, s12, 11
	s_lshl_b32 s11, s11, 8
	s_add_i32 s11, s11, s12
	v_add_u32_e32 v4, s11, v0
	s_waitcnt lgkmcnt(0)
	v_ashrrev_i32_e32 v5, 31, v4
	v_lshl_add_u64 v[4:5], v[4:5], 2, s[6:7]
	global_load_dword v235, v[4:5], off
	s_or_b64 exec, exec, s[8:9]
	s_add_i32 s10, s10, s76
	s_cmpk_gt_i32 s10, 0x1f7
	s_cbranch_scc1 .Lrs_flush_1
	s_branch .LBB0_615

; #define LAS __attribute__((address_space(3)))
; DI void fill_rs_table(const Frame& F, const pg8::Sched& S, const float* RSTD) {
;     LAS float* rs = (LAS float*)(F.lds + LDS_RS);
;     for (int i = 0; i < 9; ++i) { pg8::Unit u; if (!S.next(i, u)) break;
;         if (u.kind == 0 && F.tid < 256) rs[i * 256 + F.tid] = RSTD[u.pm * 256 + F.tid]; }
.LBB0_618:
	s_ashr_i32 s11, s11, 3
	s_add_i32 s11, s12, s11
	s_mul_hi_i32 s12, s11, 0x92492493
	s_add_i32 s12, s12, s11
	s_lshr_b32 s13, s12, 31
	s_ashr_i32 s12, s12, 5
	s_add_i32 s12, s12, s13
	s_mul_i32 s13, s12, 56
	s_sub_i32 s11, s11, s13
	s_bfe_i32 s13, s11, 0x80000
	s_bfe_u32 s13, s13, 0x3000c
	s_add_i32 s13, s11, s13
	s_and_b32 s13, s13, 0xf8
	s_sub_i32 s11, s11, s13
	s_sext_i32_i8 s11, s11
	s_lshl_b32 s12, s12, 11
	s_lshl_b32 s11, s11, 8
	s_add_i32 s11, s11, s12
	v_add_u32_e32 v4, s11, v0
	s_waitcnt lgkmcnt(0)
	v_ashrrev_i32_e32 v5, 31, v4
	v_lshl_add_u64 v[4:5], v[4:5], 2, s[6:7]
	global_load_dword v236, v[4:5], off
	s_or_b64 exec, exec, s[8:9]
	s_add_i32 s10, s10, s76
	s_cmpk_gt_i32 s10, 0x1f7
	s_cbranch_scc1 .Lrs_flush_1
	s_branch .LBB0_622

; #define LAS __attribute__((address_space(3)))
; DI void fill_rs_table(const Frame& F, const pg8::Sched& S, const float* RSTD) {
;     LAS float* rs = (LAS float*)(F.lds + LDS_RS);
;     for (int i = 0; i < 9; ++i) { pg8::Unit u; if (!S.next(i, u)) break;
;         if (u.kind == 0 && F.tid < 256) rs[i * 256 + F.tid] = RSTD[u.pm * 256 + F.tid]; }
.LBB0_625:
	s_ashr_i32 s11, s11, 3
	s_add_i32 s11, s12, s11
	s_mul_hi_i32 s12, s11, 0x92492493
	s_add_i32 s12, s12, s11
	s_lshr_b32 s13, s12, 31
	s_ashr_i32 s12, s12, 5
	s_add_i32 s12, s12, s13
	s_mul_i32 s13, s12, 56
	s_sub_i32 s11, s11, s13
	s_bfe_i32 s13, s11, 0x80000
	s_bfe_u32 s13, s13, 0x3000c
	s_add_i32 s13, s11, s13
	s_and_b32 s13, s13, 0xf8
	s_sub_i32 s11, s11, s13
	s_sext_i32_i8 s11, s11
	s_lshl_b32 s12, s12, 11
	s_lshl_b32 s11, s11, 8
	s_add_i32 s11, s11, s12
	v_add_u32_e32 v4, s11, v0
	s_waitcnt lgkmcnt(0)
	v_ashrrev_i32_e32 v5, 31, v4
	v_lshl_add_u64 v[4:5], v[4:5], 2, s[6:7]
	global_load_dword v237, v[4:5], off
	s_or_b64 exec, exec, s[8:9]
	s_add_i32 s8, s10, s76
	s_cmpk_gt_i32 s8, 0x1f7
	s_cbranch_scc1 .Lrs_flush_1
	s_branch .LBB0_629

; #define LAS __attribute__((address_space(3)))
; DI void fill_rs_table(const Frame& F, const pg8::Sched& S, const float* RSTD) {
;     LAS float* rs = (LAS float*)(F.lds + LDS_RS);
;     for (int i = 0; i < 9; ++i) { pg8::Unit u; if (!S.next(i, u)) break;
;         if (u.kind == 0 && F.tid < 256) rs[i * 256 + F.tid] = RSTD[u.pm * 256 + F.tid]; }
.LBB0_632:
	s_ashr_i32 s2, s10, 3
	s_add_i32 s2, s11, s2
	s_mul_hi_i32 s3, s2, 0x92492493
	s_add_i32 s3, s3, s2
	s_lshr_b32 s10, s3, 31
	s_ashr_i32 s3, s3, 5
	s_add_i32 s3, s3, s10
	s_mul_i32 s10, s3, 56
	s_sub_i32 s2, s2, s10
	s_bfe_i32 s10, s2, 0x80000
	s_bfe_u32 s10, s10, 0x3000c
	s_add_i32 s10, s2, s10
	s_and_b32 s10, s10, 0xf8
	s_sub_i32 s2, s2, s10
	s_sext_i32_i8 s2, s2
	s_lshl_b32 s3, s3, 11
	s_lshl_b32 s2, s2, 8
	s_add_i32 s2, s2, s3
	v_add_u32_e32 v4, s2, v0
	s_waitcnt lgkmcnt(0)
	v_ashrrev_i32_e32 v5, 31, v4
	v_lshl_add_u64 v[4:5], v[4:5], 2, s[6:7]
	global_load_dword v238, v[4:5], off

; DI unsigned xb_ld(unsigned* p)              { return __hip_atomic_load(p, __ATOMIC_RELAXED, __HIP_MEMORY_SCOPE_AGENT); }
; DI unsigned xb_add(unsigned* p, unsigned v) { return __hip_atomic_fetch_add(p, v, __ATOMIC_RELAXED, __HIP_MEMORY_SCOPE_AGENT); }
; #define XB_SPIN(cond, bar) do { unsigned _sp = 0; while (cond) { __builtin_amdgcn_s_sleep(1); \
;     if ((++_sp & 255u) == 0u) { if (xb_ld(&(bar)[XB_TMO])) break; if (_sp > XB_SPIN_CAP) { atomicAdd(&(bar)[XB_TMO], 1u); break; } } } } while (0)
; DI void xcd_barrier(const XcdBarrier& b) {
;     ...
;             __builtin_amdgcn_fence(__ATOMIC_ACQUIRE, "agent");
;             xb_add(&bar[XB_XGEN(b.x)], 1u);
;             asm volatile("s_waitcnt vmcnt(0)" ::: "memory");
;         } else {
;             XB_SPIN(xb_ld(&bar[XB_XGEN(b.x)]) == gen, bar);
;             __builtin_amdgcn_fence(__ATOMIC_ACQUIRE, "agent");
;             asm volatile("s_waitcnt vmcnt(0)" ::: "memory");
;         }
;     }
;     __syncthreads();
.LBB0_969:
	s_or_b64 exec, exec, s[6:7]
	s_waitcnt vmcnt(0)
	buffer_inv sc1
	s_waitcnt vmcnt(0)
.LBB0_970:
	s_or_b64 exec, exec, s[2:3]
	s_waitcnt lgkmcnt(0)
	s_barrier

; DI unsigned xb_ld(unsigned* p)              { return __hip_atomic_load(p, __ATOMIC_RELAXED, __HIP_MEMORY_SCOPE_AGENT); }
; DI unsigned xb_add(unsigned* p, unsigned v) { return __hip_atomic_fetch_add(p, v, __ATOMIC_RELAXED, __HIP_MEMORY_SCOPE_AGENT); }
; #define XB_SPIN(cond, bar) do { unsigned _sp = 0; while (cond) { __builtin_amdgcn_s_sleep(1); \
;     if ((++_sp & 255u) == 0u) { if (xb_ld(&(bar)[XB_TMO])) break; if (_sp > XB_SPIN_CAP) { atomicAdd(&(bar)[XB_TMO], 1u); break; } } } } while (0)
; DI void xcd_barrier(const XcdBarrier& b) {
;     ...
;             __builtin_amdgcn_fence(__ATOMIC_ACQUIRE, "agent");
;             xb_add(&bar[XB_XGEN(b.x)], 1u);
;             asm volatile("s_waitcnt vmcnt(0)" ::: "memory");
;         } else {
;             XB_SPIN(xb_ld(&bar[XB_XGEN(b.x)]) == gen, bar);
;             __builtin_amdgcn_fence(__ATOMIC_ACQUIRE, "agent");
;             asm volatile("s_waitcnt vmcnt(0)" ::: "memory");
;         }
;     }
;     __syncthreads();
.LBB0_1735:
	s_or_b64 exec, exec, s[2:3]
	s_mov_b64 s[2:3], exec
	v_mbcnt_lo_u32_b32 v3, s2, 0
	v_mbcnt_hi_u32_b32 v3, s3, v3
	v_cmp_eq_u32_e32 vcc, 0, v3
	s_and_saveexec_b64 s[4:5], vcc
	s_cbranch_execz .LBB0_1737
	s_bcnt1_i32_b64 s2, s[2:3]
	v_mov_b32_e32 v3, s2
	v_readlane_b32 s2, v253, 48
	v_readlane_b32 s3, v253, 49
	s_nop 4
	global_atomic_add v2, v3, s[2:3]
.LBB0_1737:
	s_or_b64 exec, exec, s[4:5]
	s_waitcnt vmcnt(0)
	buffer_inv sc1
	s_waitcnt vmcnt(0)
.LBB0_1738:
	s_or_b64 exec, exec, s[0:1]
	s_waitcnt lgkmcnt(0)
	s_barrier

; DI unsigned xb_ld(unsigned* p)              { return __hip_atomic_load(p, __ATOMIC_RELAXED, __HIP_MEMORY_SCOPE_AGENT); }
; DI unsigned xb_add(unsigned* p, unsigned v) { return __hip_atomic_fetch_add(p, v, __ATOMIC_RELAXED, __HIP_MEMORY_SCOPE_AGENT); }
; #define XB_SPIN(cond, bar) do { unsigned _sp = 0; while (cond) { __builtin_amdgcn_s_sleep(1); \
;     if ((++_sp & 255u) == 0u) { if (xb_ld(&(bar)[XB_TMO])) break; if (_sp > XB_SPIN_CAP) { atomicAdd(&(bar)[XB_TMO], 1u); break; } } } } while (0)
; DI void xcd_barrier(const XcdBarrier& b) {
;     ...
;             __builtin_amdgcn_fence(__ATOMIC_ACQUIRE, "agent");
;             xb_add(&bar[XB_XGEN(b.x)], 1u);
;             asm volatile("s_waitcnt vmcnt(0)" ::: "memory");
;         } else {
;             XB_SPIN(xb_ld(&bar[XB_XGEN(b.x)]) == gen, bar);
;             __builtin_amdgcn_fence(__ATOMIC_ACQUIRE, "agent");
;             asm volatile("s_waitcnt vmcnt(0)" ::: "memory");
;         }
;     }
;     __syncthreads();
.LBB0_1845:
	s_or_b64 exec, exec, s[6:7]
	s_waitcnt vmcnt(0)
	buffer_inv sc1
	s_waitcnt vmcnt(0)
.LBB0_1846:
	s_or_b64 exec, exec, s[0:1]
	s_waitcnt lgkmcnt(0)
	s_barrier

; #define LAS __attribute__((address_space(3)))
; DI unsigned xb_ld(unsigned* p)              { return __hip_atomic_load(p, __ATOMIC_RELAXED, __HIP_MEMORY_SCOPE_AGENT); }
; DI unsigned xb_add(unsigned* p, unsigned v) { return __hip_atomic_fetch_add(p, v, __ATOMIC_RELAXED, __HIP_MEMORY_SCOPE_AGENT); }
; #define XB_SPIN(cond, bar) do { unsigned _sp = 0; while (cond) { __builtin_amdgcn_s_sleep(1); \
;     if ((++_sp & 255u) == 0u) { if (xb_ld(&(bar)[XB_TMO])) break; if (_sp > XB_SPIN_CAP) { atomicAdd(&(bar)[XB_TMO], 1u); break; } } } } while (0)
; DI void xcd_barrier(const XcdBarrier& b) {
;     ...
;             __builtin_amdgcn_fence(__ATOMIC_ACQUIRE, "agent");
;             xb_add(&bar[XB_XGEN(b.x)], 1u);
;             asm volatile("s_waitcnt vmcnt(0)" ::: "memory");
;         } else {
;             XB_SPIN(xb_ld(&bar[XB_XGEN(b.x)]) == gen, bar);
;             __builtin_amdgcn_fence(__ATOMIC_ACQUIRE, "agent");
;             asm volatile("s_waitcnt vmcnt(0)" ::: "memory");
;         }
;     }
;     __syncthreads();
; DI void fill_rs_table(const Frame& F, const pg8::Sched& S, const float* RSTD) {
;     LAS float* rs = (LAS float*)(F.lds + LDS_RS);
;     for (int i = 0; i < 9; ++i) { pg8::Unit u; if (!S.next(i, u)) break;
;         if (u.kind == 0 && F.tid < 256) rs[i * 256 + F.tid] = RSTD[u.pm * 256 + F.tid]; }
.LBB0_1922:
	s_or_b64 exec, exec, s[6:7]
	s_waitcnt vmcnt(0)
	buffer_inv sc1
	s_waitcnt vmcnt(0)
.LBB0_1923:
	s_or_b64 exec, exec, s[0:1]
	s_waitcnt lgkmcnt(0)
	s_barrier
.LBB0_1924:
	s_cmp_le_i32 s70, s18
	s_cselect_b64 s[0:1], -1, 0
	s_and_b64 s[0:1], s[0:1], s[2:3]
	s_andn2_b64 vcc, exec, s[0:1]
	s_cbranch_vccnz .LBB0_1968
	s_cmpk_lt_i32 s69, 0x90
	s_cselect_b64 s[4:5], -1, 0
	s_cmpk_gt_i32 s69, 0x8f
	s_cbranch_scc1 .LBB0_1952
	s_mul_i32 s62, s90, 0x12000
	s_lshl_b64 s[2:3], s[62:63], 2
	s_add_u32 s2, s96, s2
	s_addc_u32 s3, s97, s3
	s_add_u32 s6, s2, 0x25624000
	v_readlane_b32 s2, v252, 56
	s_addc_u32 s7, s3, 0
	s_nop 0
	v_lshl_add_u32 v3, v0, 2, s2
	s_movk_i32 s2, 0xff
	v_cmp_lt_i32_e32 vcc, s2, v0
	s_movk_i32 s2, 0x100
	v_cmp_gt_i32_e64 s[2:3], s2, v0
	s_and_saveexec_b64 s[8:9], s[2:3]
	s_cbranch_execz .LBB0_1928
	s_ashr_i32 s10, s69, 31
	s_lshr_b32 s10, s10, 29
	s_add_i32 s10, s69, s10
	s_and_b32 s11, s10, -8
	s_sub_i32 s11, s69, s11
	s_cmp_lt_i32 s11, 0
	s_cselect_b32 s12, 19, 18
	s_mul_i32 s11, s11, s12
	s_ashr_i32 s10, s10, 3
	s_add_i32 s10, s11, s10
	s_ashr_i32 s11, s10, 31
	s_lshr_b32 s11, s11, 28
	s_add_i32 s11, s10, s11
	s_and_b32 s12, s11, 0xfff0
	s_sub_i32 s10, s10, s12
	s_bfe_i32 s12, s10, 0x80000
	s_bfe_u32 s12, s12, 0x3000c
	s_add_i32 s12, s10, s12
	s_and_b32 s12, s12, 0xf8
	s_sub_i32 s10, s10, s12
	s_sext_i32_i8 s10, s10
	s_lshl_b32 s11, s11, 7
	s_and_b32 s11, s11, 0xfffff800
	s_lshl_b32 s10, s10, 8
	s_add_i32 s10, s10, s11
	v_add_u32_e32 v4, s10, v0
	s_waitcnt lgkmcnt(0)
	v_ashrrev_i32_e32 v5, 31, v4
	v_lshl_add_u64 v[4:5], v[4:5], 2, s[6:7]
	global_load_dword v230, v[4:5], off
.LBB0_1928:
	s_or_b64 exec, exec, s[8:9]
	s_add_i32 s10, s69, s76
	s_cmpk_gt_i32 s10, 0x8f
	s_cbranch_scc1 .Lrs_flush_2
	s_and_saveexec_b64 s[8:9], s[2:3]
	s_cbranch_execz .LBB0_1931
	s_ashr_i32 s11, s10, 31
	s_lshr_b32 s11, s11, 29
	s_add_i32 s11, s10, s11
	s_ashr_i32 s12, s11, 3
	s_and_b32 s11, s11, -8
	s_sub_i32 s11, s10, s11
	s_cmp_lt_i32 s11, 0
	s_cselect_b32 s13, 19, 18
	s_mul_i32 s11, s11, s13
	s_add_i32 s11, s11, s12
	s_ashr_i32 s12, s11, 31
	s_lshr_b32 s12, s12, 28
	s_add_i32 s12, s11, s12
	s_and_b32 s13, s12, 0xfff0
	s_sub_i32 s11, s11, s13
	s_bfe_i32 s13, s11, 0x80000
	s_bfe_u32 s13, s13, 0x3000c
	s_add_i32 s13, s11, s13
	s_and_b32 s13, s13, 0xf8
	s_sub_i32 s11, s11, s13
	s_sext_i32_i8 s11, s11
	s_lshl_b32 s12, s12, 7
	s_and_b32 s12, s12, 0xfffff800
	s_lshl_b32 s11, s11, 8
	s_add_i32 s11, s11, s12
	v_add_u32_e32 v4, s11, v0
	s_waitcnt lgkmcnt(0)
	v_ashrrev_i32_e32 v5, 31, v4
	v_lshl_add_u64 v[4:5], v[4:5], 2, s[6:7]
	global_load_dword v231, v[4:5], off
.LBB0_1931:
	s_or_b64 exec, exec, s[8:9]
	s_add_i32 s10, s10, s76
	s_cmpk_gt_i32 s10, 0x8f
	s_cbranch_scc1 .Lrs_flush_2
	s_and_saveexec_b64 s[8:9], s[2:3]
	s_cbranch_execz .LBB0_1934
	s_ashr_i32 s11, s10, 31
	s_lshr_b32 s11, s11, 29
	s_add_i32 s11, s10, s11
	s_ashr_i32 s12, s11, 3
	s_and_b32 s11, s11, -8
	s_sub_i32 s11, s10, s11
	s_cmp_lt_i32 s11, 0
	s_cselect_b32 s13, 19, 18
	s_mul_i32 s11, s11, s13
	s_add_i32 s11, s11, s12
	s_ashr_i32 s12, s11, 31
	s_lshr_b32 s12, s12, 28
	s_add_i32 s12, s11, s12
	s_and_b32 s13, s12, 0xfff0
	s_sub_i32 s11, s11, s13
	s_bfe_i32 s13, s11, 0x80000
	s_bfe_u32 s13, s13, 0x3000c
	s_add_i32 s13, s11, s13
	s_and_b32 s13, s13, 0xf8
	s_sub_i32 s11, s11, s13
	s_sext_i32_i8 s11, s11
	s_lshl_b32 s12, s12, 7
	s_and_b32 s12, s12, 0xfffff800
	s_lshl_b32 s11, s11, 8
	s_add_i32 s11, s11, s12
	v_add_u32_e32 v4, s11, v0
	s_waitcnt lgkmcnt(0)
	v_ashrrev_i32_e32 v5, 31, v4
	v_lshl_add_u64 v[4:5], v[4:5], 2, s[6:7]
	global_load_dword v232, v[4:5], off
.LBB0_1934:
	s_or_b64 exec, exec, s[8:9]
	s_add_i32 s10, s10, s76
	s_cmpk_gt_i32 s10, 0x8f
	s_cbranch_scc1 .Lrs_flush_2
	s_and_saveexec_b64 s[8:9], s[2:3]
	s_cbranch_execz .LBB0_1937
	s_ashr_i32 s11, s10, 31
	s_lshr_b32 s11, s11, 29
	s_add_i32 s11, s10, s11
	s_ashr_i32 s12, s11, 3
	s_and_b32 s11, s11, -8
	s_sub_i32 s11, s10, s11
	s_cmp_lt_i32 s11, 0
	s_cselect_b32 s13, 19, 18
	s_mul_i32 s11, s11, s13
	s_add_i32 s11, s11, s12
	s_ashr_i32 s12, s11, 31
	s_lshr_b32 s12, s12, 28
	s_add_i32 s12, s11, s12
	s_and_b32 s13, s12, 0xfff0
	s_sub_i32 s11, s11, s13
	s_bfe_i32 s13, s11, 0x80000
	s_bfe_u32 s13, s13, 0x3000c
	s_add_i32 s13, s11, s13
	s_and_b32 s13, s13, 0xf8
	s_sub_i32 s11, s11, s13
	s_sext_i32_i8 s11, s11
	s_lshl_b32 s12, s12, 7
	s_and_b32 s12, s12, 0xfffff800
	s_lshl_b32 s11, s11, 8
	s_add_i32 s11, s11, s12
	v_add_u32_e32 v4, s11, v0
	s_waitcnt lgkmcnt(0)
	v_ashrrev_i32_e32 v5, 31, v4
	v_lshl_add_u64 v[4:5], v[4:5], 2, s[6:7]
	global_load_dword v233, v[4:5], off
; #define LAS __attribute__((address_space(3)))
; DI void fill_rs_table(const Frame& F, const pg8::Sched& S, const float* RSTD) {
;     LAS float* rs = (LAS float*)(F.lds + LDS_RS);
;     for (int i = 0; i < 9; ++i) { pg8::Unit u; if (!S.next(i, u)) break;
;         if (u.kind == 0 && F.tid < 256) rs[i * 256 + F.tid] = RSTD[u.pm * 256 + F.tid]; }
.LBB0_1937:
	s_or_b64 exec, exec, s[8:9]
	s_add_i32 s10, s10, s76
	s_cmpk_gt_i32 s10, 0x8f
	s_cbranch_scc1 .Lrs_flush_2
	s_and_saveexec_b64 s[8:9], s[2:3]
	s_cbranch_execz .LBB0_1940
	s_ashr_i32 s11, s10, 31
	s_lshr_b32 s11, s11, 29
	s_add_i32 s11, s10, s11
	s_ashr_i32 s12, s11, 3
	s_and_b32 s11, s11, -8
	s_sub_i32 s11, s10, s11
	s_cmp_lt_i32 s11, 0
	s_cselect_b32 s13, 19, 18
	s_mul_i32 s11, s11, s13
	s_add_i32 s11, s11, s12
	s_ashr_i32 s12, s11, 31
	s_lshr_b32 s12, s12, 28
	s_add_i32 s12, s11, s12
	s_and_b32 s13, s12, 0xfff0
	s_sub_i32 s11, s11, s13
	s_bfe_i32 s13, s11, 0x80000
	s_bfe_u32 s13, s13, 0x3000c
	s_add_i32 s13, s11, s13
	s_and_b32 s13, s13, 0xf8
	s_sub_i32 s11, s11, s13
	s_sext_i32_i8 s11, s11
	s_lshl_b32 s12, s12, 7
	s_and_b32 s12, s12, 0xfffff800
	s_lshl_b32 s11, s11, 8
	s_add_i32 s11, s11, s12
	v_add_u32_e32 v4, s11, v0
	s_waitcnt lgkmcnt(0)
	v_ashrrev_i32_e32 v5, 31, v4
	v_lshl_add_u64 v[4:5], v[4:5], 2, s[6:7]
	global_load_dword v234, v[4:5], off
.LBB0_1940:
	s_or_b64 exec, exec, s[8:9]
	s_add_i32 s10, s10, s76
	s_cmpk_gt_i32 s10, 0x8f
	s_cbranch_scc1 .Lrs_flush_2
	s_and_saveexec_b64 s[8:9], s[2:3]
	s_cbranch_execz .LBB0_1943
	s_ashr_i32 s11, s10, 31
	s_lshr_b32 s11, s11, 29
	s_add_i32 s11, s10, s11
	s_ashr_i32 s12, s11, 3
	s_and_b32 s11, s11, -8
	s_sub_i32 s11, s10, s11
	s_cmp_lt_i32 s11, 0
	s_cselect_b32 s13, 19, 18
	s_mul_i32 s11, s11, s13
	s_add_i32 s11, s11, s12
	s_ashr_i32 s12, s11, 31
	s_lshr_b32 s12, s12, 28
	s_add_i32 s12, s11, s12
	s_and_b32 s13, s12, 0xfff0
	s_sub_i32 s11, s11, s13
	s_bfe_i32 s13, s11, 0x80000
	s_bfe_u32 s13, s13, 0x3000c
	s_add_i32 s13, s11, s13
	s_and_b32 s13, s13, 0xf8
	s_sub_i32 s11, s11, s13
	s_sext_i32_i8 s11, s11
	s_lshl_b32 s12, s12, 7
	s_and_b32 s12, s12, 0xfffff800
	s_lshl_b32 s11, s11, 8
	s_add_i32 s11, s11, s12
	v_add_u32_e32 v4, s11, v0
	s_waitcnt lgkmcnt(0)
	v_ashrrev_i32_e32 v5, 31, v4
	v_lshl_add_u64 v[4:5], v[4:5], 2, s[6:7]
	global_load_dword v235, v[4:5], off
.LBB0_1943:
	s_or_b64 exec, exec, s[8:9]
	s_add_i32 s10, s10, s76
	s_cmpk_gt_i32 s10, 0x8f
	s_cbranch_scc1 .Lrs_flush_2
	s_and_saveexec_b64 s[8:9], s[2:3]
	s_cbranch_execz .LBB0_1946
	s_ashr_i32 s11, s10, 31
	s_lshr_b32 s11, s11, 29
	s_add_i32 s11, s10, s11
	s_ashr_i32 s12, s11, 3
	s_and_b32 s11, s11, -8
	s_sub_i32 s11, s10, s11
	s_cmp_lt_i32 s11, 0
	s_cselect_b32 s13, 19, 18
	s_mul_i32 s11, s11, s13
	s_add_i32 s11, s11, s12
	s_ashr_i32 s12, s11, 31
	s_lshr_b32 s12, s12, 28
	s_add_i32 s12, s11, s12
	s_and_b32 s13, s12, 0xfff0
	s_sub_i32 s11, s11, s13
	s_bfe_i32 s13, s11, 0x80000
	s_bfe_u32 s13, s13, 0x3000c
	s_add_i32 s13, s11, s13
	s_and_b32 s13, s13, 0xf8
	s_sub_i32 s11, s11, s13
	s_sext_i32_i8 s11, s11
	s_lshl_b32 s12, s12, 7
	s_and_b32 s12, s12, 0xfffff800
	s_lshl_b32 s11, s11, 8
	s_add_i32 s11, s11, s12
	v_add_u32_e32 v4, s11, v0
	s_waitcnt lgkmcnt(0)
	v_ashrrev_i32_e32 v5, 31, v4
	v_lshl_add_u64 v[4:5], v[4:5], 2, s[6:7]
	global_load_dword v236, v[4:5], off
.LBB0_1946:
	s_or_b64 exec, exec, s[8:9]
	s_add_i32 s10, s10, s76
	s_cmpk_gt_i32 s10, 0x8f
	s_cbranch_scc1 .Lrs_flush_2
	s_and_saveexec_b64 s[8:9], s[2:3]
	s_cbranch_execz .LBB0_1949
	s_ashr_i32 s2, s10, 31
	s_lshr_b32 s2, s2, 29
	s_add_i32 s2, s10, s2
	s_ashr_i32 s3, s2, 3
	s_and_b32 s2, s2, -8
	s_sub_i32 s2, s10, s2
	s_cmp_lt_i32 s2, 0
	s_cselect_b32 s11, 19, 18
	s_mul_i32 s2, s2, s11
	s_add_i32 s2, s2, s3
	s_ashr_i32 s3, s2, 31
	s_lshr_b32 s3, s3, 28
	s_add_i32 s3, s2, s3
	s_and_b32 s11, s3, 0xfff0
	s_sub_i32 s2, s2, s11
	s_bfe_i32 s11, s2, 0x80000
	s_bfe_u32 s11, s11, 0x3000c
	s_add_i32 s11, s2, s11
	s_and_b32 s11, s11, 0xf8
	s_sub_i32 s2, s2, s11
	s_sext_i32_i8 s2, s2
	s_lshl_b32 s3, s3, 7
	s_and_b32 s3, s3, 0xfffff800
	s_lshl_b32 s2, s2, 8
	s_add_i32 s2, s2, s3
	v_add_u32_e32 v4, s2, v0
	s_waitcnt lgkmcnt(0)
	v_ashrrev_i32_e32 v5, 31, v4
	v_lshl_add_u64 v[4:5], v[4:5], 2, s[6:7]
	global_load_dword v237, v[4:5], off
.LBB0_1949:
	s_or_b64 exec, exec, s[8:9]
	s_add_i32 s8, s10, s76
	s_cmpk_lt_i32 s8, 0x90
	s_cselect_b64 s[2:3], -1, 0
	s_xor_b64 s[10:11], vcc, -1
	s_and_b64 s[10:11], s[2:3], s[10:11]
	s_and_saveexec_b64 s[2:3], s[10:11]
	s_cbranch_execz .LBB0_1951
	s_ashr_i32 s9, s8, 31
	s_lshr_b32 s9, s9, 29
	s_add_i32 s9, s8, s9
	s_ashr_i32 s10, s9, 3
	s_and_b32 s9, s9, -8
	s_sub_i32 s8, s8, s9
	s_cmp_lt_i32 s8, 0
	s_cselect_b32 s9, 19, 18
	s_mul_i32 s8, s8, s9
	s_add_i32 s8, s8, s10
	s_ashr_i32 s9, s8, 31
	s_lshr_b32 s9, s9, 28
	s_add_i32 s9, s8, s9
	s_and_b32 s10, s9, 0xfff0
	s_sub_i32 s8, s8, s10
	s_bfe_i32 s10, s8, 0x80000
	s_bfe_u32 s10, s10, 0x3000c
	s_add_i32 s10, s8, s10
	s_and_b32 s10, s10, 0xf8
	s_sub_i32 s8, s8, s10
	s_sext_i32_i8 s8, s8
	s_lshl_b32 s9, s9, 7
	s_and_b32 s9, s9, 0xfffff800
	s_lshl_b32 s8, s8, 8
	s_add_i32 s8, s8, s9
	v_add_u32_e32 v4, s8, v0
	s_waitcnt lgkmcnt(0)
	v_ashrrev_i32_e32 v5, 31, v4
	v_lshl_add_u64 v[4:5], v[4:5], 2, s[6:7]
	global_load_dword v238, v[4:5], off

; DI unsigned xb_ld(unsigned* p)              { return __hip_atomic_load(p, __ATOMIC_RELAXED, __HIP_MEMORY_SCOPE_AGENT); }
; DI unsigned xb_add(unsigned* p, unsigned v) { return __hip_atomic_fetch_add(p, v, __ATOMIC_RELAXED, __HIP_MEMORY_SCOPE_AGENT); }
; #define XB_SPIN(cond, bar) do { unsigned _sp = 0; while (cond) { __builtin_amdgcn_s_sleep(1); \
;     if ((++_sp & 255u) == 0u) { if (xb_ld(&(bar)[XB_TMO])) break; if (_sp > XB_SPIN_CAP) { atomicAdd(&(bar)[XB_TMO], 1u); break; } } } } while (0)
; DI void xcd_barrier(const XcdBarrier& b) {
;     ...
;             __builtin_amdgcn_fence(__ATOMIC_ACQUIRE, "agent");
;             xb_add(&bar[XB_XGEN(b.x)], 1u);
;             asm volatile("s_waitcnt vmcnt(0)" ::: "memory");
;         } else {
;             XB_SPIN(xb_ld(&bar[XB_XGEN(b.x)]) == gen, bar);
;             __builtin_amdgcn_fence(__ATOMIC_ACQUIRE, "agent");
;             asm volatile("s_waitcnt vmcnt(0)" ::: "memory");
;         }
;     }
;     __syncthreads();
.LBB0_2020:
	s_or_b64 exec, exec, s[6:7]
	s_waitcnt vmcnt(0)
	buffer_inv sc1
	s_waitcnt vmcnt(0)
.LBB0_2021:
	s_or_b64 exec, exec, s[0:1]
	s_waitcnt lgkmcnt(0)
	s_barrier

; DI unsigned xb_ld(unsigned* p)              { return __hip_atomic_load(p, __ATOMIC_RELAXED, __HIP_MEMORY_SCOPE_AGENT); }
; DI unsigned xb_add(unsigned* p, unsigned v) { return __hip_atomic_fetch_add(p, v, __ATOMIC_RELAXED, __HIP_MEMORY_SCOPE_AGENT); }
; #define XB_SPIN(cond, bar) do { unsigned _sp = 0; while (cond) { __builtin_amdgcn_s_sleep(1); \
;     if ((++_sp & 255u) == 0u) { if (xb_ld(&(bar)[XB_TMO])) break; if (_sp > XB_SPIN_CAP) { atomicAdd(&(bar)[XB_TMO], 1u); break; } } } } while (0)
; DI void xcd_barrier(const XcdBarrier& b) {
;     ...
;             __builtin_amdgcn_fence(__ATOMIC_ACQUIRE, "agent");
;             xb_add(&bar[XB_XGEN(b.x)], 1u);
;             asm volatile("s_waitcnt vmcnt(0)" ::: "memory");
;         } else {
;             XB_SPIN(xb_ld(&bar[XB_XGEN(b.x)]) == gen, bar);
;             __builtin_amdgcn_fence(__ATOMIC_ACQUIRE, "agent");
;             asm volatile("s_waitcnt vmcnt(0)" ::: "memory");
;         }
;     }
;     __syncthreads();
.LBB0_2097:
	s_or_b64 exec, exec, s[6:7]
	s_waitcnt vmcnt(0)
	buffer_inv sc1
	s_waitcnt vmcnt(0)
.LBB0_2098:
	s_or_b64 exec, exec, s[2:3]
	s_waitcnt lgkmcnt(0)
	s_barrier

; DI unsigned xb_ld(unsigned* p)              { return __hip_atomic_load(p, __ATOMIC_RELAXED, __HIP_MEMORY_SCOPE_AGENT); }
; DI unsigned xb_add(unsigned* p, unsigned v) { return __hip_atomic_fetch_add(p, v, __ATOMIC_RELAXED, __HIP_MEMORY_SCOPE_AGENT); }
; #define XB_SPIN(cond, bar) do { unsigned _sp = 0; while (cond) { __builtin_amdgcn_s_sleep(1); \
;     if ((++_sp & 255u) == 0u) { if (xb_ld(&(bar)[XB_TMO])) break; if (_sp > XB_SPIN_CAP) { atomicAdd(&(bar)[XB_TMO], 1u); break; } } } } while (0)
; DI void xcd_barrier(const XcdBarrier& b) {
;     ...
;             __builtin_amdgcn_fence(__ATOMIC_ACQUIRE, "agent");
;             xb_add(&bar[XB_XGEN(b.x)], 1u);
;             asm volatile("s_waitcnt vmcnt(0)" ::: "memory");
;         } else {
;             XB_SPIN(xb_ld(&bar[XB_XGEN(b.x)]) == gen, bar);
;             __builtin_amdgcn_fence(__ATOMIC_ACQUIRE, "agent");
;             asm volatile("s_waitcnt vmcnt(0)" ::: "memory");
;         }
;     }
;     __syncthreads();
.LBB0_2205:
	s_or_b64 exec, exec, s[6:7]
	s_waitcnt vmcnt(0)
	buffer_inv sc1
	s_waitcnt vmcnt(0)
.LBB0_2206:
	s_or_b64 exec, exec, s[0:1]
	s_waitcnt lgkmcnt(0)
	s_barrier

; #define LAS __attribute__((address_space(3)))
; DI unsigned xb_ld(unsigned* p)              { return __hip_atomic_load(p, __ATOMIC_RELAXED, __HIP_MEMORY_SCOPE_AGENT); }
; DI unsigned xb_add(unsigned* p, unsigned v) { return __hip_atomic_fetch_add(p, v, __ATOMIC_RELAXED, __HIP_MEMORY_SCOPE_AGENT); }
; #define XB_SPIN(cond, bar) do { unsigned _sp = 0; while (cond) { __builtin_amdgcn_s_sleep(1); \
;     if ((++_sp & 255u) == 0u) { if (xb_ld(&(bar)[XB_TMO])) break; if (_sp > XB_SPIN_CAP) { atomicAdd(&(bar)[XB_TMO], 1u); break; } } } } while (0)
; DI void xcd_barrier(const XcdBarrier& b) {
;     ...
;             __builtin_amdgcn_fence(__ATOMIC_ACQUIRE, "agent");
;             xb_add(&bar[XB_XGEN(b.x)], 1u);
;             asm volatile("s_waitcnt vmcnt(0)" ::: "memory");
;         } else {
;             XB_SPIN(xb_ld(&bar[XB_XGEN(b.x)]) == gen, bar);
;             __builtin_amdgcn_fence(__ATOMIC_ACQUIRE, "agent");
;             asm volatile("s_waitcnt vmcnt(0)" ::: "memory");
;         }
;     }
;     __syncthreads();
; DI void fill_rs_table(const Frame& F, const pg8::Sched& S, const float* RSTD) {
;     LAS float* rs = (LAS float*)(F.lds + LDS_RS);
;     for (int i = 0; i < 9; ++i) { pg8::Unit u; if (!S.next(i, u)) break;
;         if (u.kind == 0 && F.tid < 256) rs[i * 256 + F.tid] = RSTD[u.pm * 256 + F.tid]; }
.LBB0_2282:
	s_or_b64 exec, exec, s[6:7]
	s_waitcnt vmcnt(0)
	buffer_inv sc1
	s_waitcnt vmcnt(0)
.LBB0_2283:
	s_or_b64 exec, exec, s[0:1]
	s_waitcnt lgkmcnt(0)
	s_barrier
.LBB0_2284:
	s_cmp_le_i32 s70, s18
	s_cselect_b64 s[0:1], -1, 0
	s_and_b64 s[0:1], s[0:1], s[2:3]
	s_andn2_b64 vcc, exec, s[0:1]
	s_cbranch_vccnz .LBB0_2328
	s_cmpk_lt_i32 s69, 0x900
	s_cselect_b64 s[4:5], -1, 0
	s_cmpk_gt_i32 s69, 0x8ff
	s_cbranch_scc1 .LBB0_2312
	s_mul_i32 s62, s90, 0x12000
	s_lshl_b64 s[2:3], s[62:63], 2
	s_add_u32 s2, s96, s2
	s_addc_u32 s3, s97, s3
	s_add_u32 s6, s2, 0x25636000
	v_readlane_b32 s2, v252, 56
	s_addc_u32 s7, s3, 0
	s_nop 0
	v_lshl_add_u32 v3, v0, 2, s2
	s_movk_i32 s2, 0xff
	v_cmp_lt_i32_e32 vcc, s2, v0
	s_movk_i32 s2, 0x100
	v_cmp_gt_i32_e64 s[2:3], s2, v0
	s_and_saveexec_b64 s[8:9], s[2:3]
	s_cbranch_execz .LBB0_2288
	s_ashr_i32 s10, s69, 31
	s_lshr_b32 s10, s10, 29
	s_add_i32 s10, s69, s10
	s_and_b32 s11, s10, -8
	s_sub_i32 s11, s69, s11
	s_cmp_lt_i32 s11, 0
	s_movk_i32 s12, 0x121
	s_cselect_b32 s12, s12, 0x120
	s_mul_i32 s11, s11, s12
	s_ashr_i32 s10, s10, 3
	s_add_i32 s10, s11, s10
	s_ashr_i32 s11, s10, 31
	s_lshr_b32 s11, s11, 24
	s_add_i32 s11, s10, s11
	s_and_b32 s12, s11, 0xff00
	s_sub_i32 s10, s10, s12
	s_sext_i32_i16 s12, s10
	s_bfe_u32 s12, s12, 0x3001c
	s_add_i32 s12, s10, s12
	s_and_b32 s12, s12, 0xfff8
	s_sub_i32 s10, s10, s12
	s_sext_i32_i16 s10, s10
	s_lshl_b32 s11, s11, 3
	s_and_b32 s11, s11, 0xfffff800
	s_lshl_b32 s10, s10, 8
	s_add_i32 s10, s10, s11
	v_add_u32_e32 v4, s10, v0
	s_waitcnt lgkmcnt(0)
	v_ashrrev_i32_e32 v5, 31, v4
	v_lshl_add_u64 v[4:5], v[4:5], 2, s[6:7]
	global_load_dword v230, v[4:5], off

; DI unsigned xb_ld(unsigned* p)              { return __hip_atomic_load(p, __ATOMIC_RELAXED, __HIP_MEMORY_SCOPE_AGENT); }
; DI unsigned xb_add(unsigned* p, unsigned v) { return __hip_atomic_fetch_add(p, v, __ATOMIC_RELAXED, __HIP_MEMORY_SCOPE_AGENT); }
; #define XB_SPIN(cond, bar) do { unsigned _sp = 0; while (cond) { __builtin_amdgcn_s_sleep(1); \
;     if ((++_sp & 255u) == 0u) { if (xb_ld(&(bar)[XB_TMO])) break; if (_sp > XB_SPIN_CAP) { atomicAdd(&(bar)[XB_TMO], 1u); break; } } } } while (0)
; DI void xcd_barrier(const XcdBarrier& b) {
;     ...
;             __builtin_amdgcn_fence(__ATOMIC_ACQUIRE, "agent");
;             xb_add(&bar[XB_XGEN(b.x)], 1u);
;             asm volatile("s_waitcnt vmcnt(0)" ::: "memory");
;         } else {
;             XB_SPIN(xb_ld(&bar[XB_XGEN(b.x)]) == gen, bar);
;             __builtin_amdgcn_fence(__ATOMIC_ACQUIRE, "agent");
;             asm volatile("s_waitcnt vmcnt(0)" ::: "memory");
;         }
;     }
;     __syncthreads();
.LBB0_2380:
	s_or_b64 exec, exec, s[6:7]
	s_waitcnt vmcnt(0)
	buffer_inv sc1
	s_waitcnt vmcnt(0)
.LBB0_2381:
	s_or_b64 exec, exec, s[0:1]
	s_waitcnt lgkmcnt(0)
	s_barrier

; __global__ void __launch_bounds__(NTHR, 2) fwd(Args args) {
;     extern __shared__ __attribute__((aligned(16))) unsigned char lds_raw[];
	.amdhsa_kernel _Z3fwd4Args
		.amdhsa_group_segment_fixed_size 0
		.amdhsa_private_segment_fixed_size 0
		.amdhsa_kernarg_size 696
		.amdhsa_user_sgpr_count 2
		.amdhsa_user_sgpr_dispatch_ptr 0
		.amdhsa_user_sgpr_queue_ptr 0
		.amdhsa_user_sgpr_kernarg_segment_ptr 1
		.amdhsa_user_sgpr_dispatch_id 0
		.amdhsa_user_sgpr_kernarg_preload_length 0
		.amdhsa_user_sgpr_kernarg_preload_offset 0
		.amdhsa_user_sgpr_private_segment_size 0
		.amdhsa_uses_dynamic_stack 0
		.amdhsa_enable_private_segment 0
		.amdhsa_system_sgpr_workgroup_id_x 1
		.amdhsa_system_sgpr_workgroup_id_y 0
		.amdhsa_system_sgpr_workgroup_id_z 0
		.amdhsa_system_sgpr_workgroup_info 0
		.amdhsa_system_vgpr_workitem_id 0
		.amdhsa_next_free_vgpr 254
		.amdhsa_next_free_sgpr 102
		.amdhsa_accum_offset 256
		.amdhsa_reserve_vcc 1
		.amdhsa_float_round_mode_32 0
		.amdhsa_float_round_mode_16_64 0
		.amdhsa_float_denorm_mode_32 3
		.amdhsa_float_denorm_mode_16_64 3
		.amdhsa_dx10_clamp 1
		.amdhsa_ieee_mode 1
		.amdhsa_fp16_overflow 0
		.amdhsa_tg_split 0
		.amdhsa_exception_fp_ieee_invalid_op 0
		.amdhsa_exception_fp_denorm_src 0
		.amdhsa_exception_fp_ieee_div_zero 0
		.amdhsa_exception_fp_ieee_overflow 0
		.amdhsa_exception_fp_ieee_underflow 0
		.amdhsa_exception_fp_ieee_inexact 0
		.amdhsa_exception_int_div_zero 0
	.end_amdhsa_kernel

; __global__ void __launch_bounds__(NTHR, 2) fwd(Args args) {
;     extern __shared__ __attribute__((aligned(16))) unsigned char lds_raw[];
amdhsa.kernels:
  - .agpr_count:     0
    .args:
      - .offset:         0
        .size:           440
        .value_kind:     by_value
      - .offset:         440
        .size:           4
        .value_kind:     hidden_block_count_x
      - .offset:         444
        .size:           4
        .value_kind:     hidden_block_count_y
      - .offset:         448
        .size:           4
        .value_kind:     hidden_block_count_z
      - .offset:         452
        .size:           2
        .value_kind:     hidden_group_size_x
      - .offset:         454
        .size:           2
        .value_kind:     hidden_group_size_y
      - .offset:         456
        .size:           2
        .value_kind:     hidden_group_size_z
      - .offset:         458
        .size:           2
        .value_kind:     hidden_remainder_x
      - .offset:         460
        .size:           2
        .value_kind:     hidden_remainder_y
      - .offset:         462
        .size:           2
        .value_kind:     hidden_remainder_z
      - .offset:         480
        .size:           8
        .value_kind:     hidden_global_offset_x
      - .offset:         488
        .size:           8
        .value_kind:     hidden_global_offset_y
      - .offset:         496
        .size:           8
        .value_kind:     hidden_global_offset_z
      - .offset:         504
        .size:           2
        .value_kind:     hidden_grid_dims
      - .offset:         560
        .size:           4
        .value_kind:     hidden_dynamic_lds_size
    .group_segment_fixed_size: 0
    .kernarg_segment_align: 8
    .kernarg_segment_size: 696
    .language:       OpenCL C
    .language_version:
      - 2
      - 0
    .max_flat_workgroup_size: 512
    .name:           _Z3fwd4Args
    .private_segment_fixed_size: 0
    .sgpr_count:     108
    .sgpr_spill_count: 400
    .symbol:         _Z3fwd4Args.kd
    .uniform_work_group_size: 1
    .uses_dynamic_stack: false
    .vgpr_count:     254
    .vgpr_spill_count: 0
    .wavefront_size: 64
